# up-projection tile prelude: all 32 row loads per wave issued up front, two 16-row reductions behind counted waits
# baseline (speedup 1.0000x reference)
; #define LAS __attribute__((address_space(3)))
; __device__ __forceinline__ float bf2f(unsigned short b) { return __uint_as_float(((unsigned)b) << 16); }
; __device__ __forceinline__ void up_phase(const bf16_t* cqkv, const bf16_t* wqb, const bf16_t* wkvb, EpiUp& epi) {
;     ...
;     const int brow = pm * BM; const bool isq = pn < 3;
;     LAS float* rsb = (LAS float*)(lds_raw + RS_OFF);
;     const bf16_t* rp = cqkv + (size_t)(brow + wid * 32) * 512 + (isq ? lane * 4 : 256 + lane * 2);
;     for (int r0 = 0; r0 < 32; r0 += 16) {
;       u32x2 wv[16];
; #pragma unroll
;       for (int rr = 0; rr < 16; ++rr) { if (isq) wv[rr] = *(const u32x2*)(rp + (size_t)(r0 + rr) * 512); else { wv[rr].x = *(const unsigned*)(rp + (size_t)(r0 + rr) * 512); wv[rr].y = 0u; } }
; #pragma unroll
;       for (int rr = 0; rr < 16; ++rr) {
;         const float a = bf2f(wv[rr].x & 0xffff), b = bf2f(wv[rr].x >> 16), c = bf2f(wv[rr].y & 0xffff), d = bf2f(wv[rr].y >> 16);
;         const float ss = wave_sum(a * a + b * b + c * c + d * d);
;         if (lane == 0) rsb[wid * 32 + r0 + rr] = rsqrtf(ss * (isq ? 1.0f / 256.0f : 1.0f / 128.0f) + 1e-6f);
;       }
;     }
.LBB0_844:
	s_waitcnt lgkmcnt(0)
	s_mov_b64 s[8:9], 0x1000
	v_lshl_add_u64 v[92:93], v[2:3], 0, s[8:9]
	s_mov_b64 s[8:9], 0x2000
	v_lshl_add_u64 v[94:95], v[2:3], 0, s[8:9]
	s_mov_b64 s[8:9], 0x3000
	v_lshl_add_u64 v[96:97], v[2:3], 0, s[8:9]
	s_mov_b64 s[8:9], 0x4000
	v_lshl_add_u64 v[98:99], v[2:3], 0, s[8:9]
	s_mov_b64 s[8:9], 0x5000
	v_lshl_add_u64 v[100:101], v[2:3], 0, s[8:9]
	s_mov_b64 s[8:9], 0x6000
	v_lshl_add_u64 v[102:103], v[2:3], 0, s[8:9]
	s_mov_b64 s[8:9], 0x7000
	v_lshl_add_u64 v[104:105], v[2:3], 0, s[8:9]
	s_and_b64 vcc, exec, s[6:7]
	s_cbranch_vccnz .Lup_kvld
	global_load_dwordx2 v[32:33], v[2:3], off
	global_load_dwordx2 v[34:35], v[2:3], off offset:1024
	global_load_dwordx2 v[30:31], v[2:3], off offset:2048
	global_load_dwordx2 v[28:29], v[2:3], off offset:3072
	global_load_dwordx2 v[26:27], v[92:93], off
	global_load_dwordx2 v[24:25], v[92:93], off offset:1024
	global_load_dwordx2 v[22:23], v[92:93], off offset:2048
	global_load_dwordx2 v[20:21], v[92:93], off offset:3072
	global_load_dwordx2 v[18:19], v[94:95], off
	global_load_dwordx2 v[16:17], v[94:95], off offset:1024
	global_load_dwordx2 v[14:15], v[94:95], off offset:2048
	global_load_dwordx2 v[12:13], v[94:95], off offset:3072
	global_load_dwordx2 v[10:11], v[96:97], off
	global_load_dwordx2 v[8:9], v[96:97], off offset:1024
	global_load_dwordx2 v[6:7], v[96:97], off offset:2048
	global_load_dwordx2 v[4:5], v[96:97], off offset:3072
	global_load_dwordx2 v[56:57], v[98:99], off
	global_load_dwordx2 v[58:59], v[98:99], off offset:1024
	global_load_dwordx2 v[60:61], v[98:99], off offset:2048
	global_load_dwordx2 v[62:63], v[98:99], off offset:3072
	global_load_dwordx2 v[64:65], v[100:101], off
	global_load_dwordx2 v[66:67], v[100:101], off offset:1024
	global_load_dwordx2 v[68:69], v[100:101], off offset:2048
	global_load_dwordx2 v[70:71], v[100:101], off offset:3072
	global_load_dwordx2 v[72:73], v[102:103], off
	global_load_dwordx2 v[74:75], v[102:103], off offset:1024
	global_load_dwordx2 v[76:77], v[102:103], off offset:2048
	global_load_dwordx2 v[78:79], v[102:103], off offset:3072
	global_load_dwordx2 v[80:81], v[104:105], off
	global_load_dwordx2 v[82:83], v[104:105], off offset:1024
	global_load_dwordx2 v[84:85], v[104:105], off offset:2048
	global_load_dwordx2 v[88:89], v[104:105], off offset:3072
	s_branch .Lup_ldone
.Lup_kvld:
	v_mov_b32_e32 v33, 0
	v_mov_b32_e32 v35, 0
	v_mov_b32_e32 v31, 0
	v_mov_b32_e32 v29, 0
	v_mov_b32_e32 v27, 0
	v_mov_b32_e32 v25, 0
	v_mov_b32_e32 v23, 0
	v_mov_b32_e32 v21, 0
	v_mov_b32_e32 v19, 0
	v_mov_b32_e32 v17, 0
	v_mov_b32_e32 v15, 0
	v_mov_b32_e32 v13, 0
	v_mov_b32_e32 v11, 0
	v_mov_b32_e32 v9, 0
	v_mov_b32_e32 v7, 0
	v_mov_b32_e32 v5, 0
	v_mov_b32_e32 v57, 0
	v_mov_b32_e32 v59, 0
	v_mov_b32_e32 v61, 0
	v_mov_b32_e32 v63, 0
	v_mov_b32_e32 v65, 0
	v_mov_b32_e32 v67, 0
	v_mov_b32_e32 v69, 0
	v_mov_b32_e32 v71, 0
	v_mov_b32_e32 v73, 0
	v_mov_b32_e32 v75, 0
	v_mov_b32_e32 v77, 0
	v_mov_b32_e32 v79, 0
	v_mov_b32_e32 v81, 0
	v_mov_b32_e32 v83, 0
	v_mov_b32_e32 v85, 0
	v_mov_b32_e32 v89, 0
	global_load_dword v32, v[2:3], off
	global_load_dword v34, v[2:3], off offset:1024
	global_load_dword v30, v[2:3], off offset:2048
	global_load_dword v28, v[2:3], off offset:3072
	global_load_dword v26, v[92:93], off
	global_load_dword v24, v[92:93], off offset:1024
	global_load_dword v22, v[92:93], off offset:2048
	global_load_dword v20, v[92:93], off offset:3072
	global_load_dword v18, v[94:95], off
	global_load_dword v16, v[94:95], off offset:1024
	global_load_dword v14, v[94:95], off offset:2048
	global_load_dword v12, v[94:95], off offset:3072
	global_load_dword v10, v[96:97], off
	global_load_dword v8, v[96:97], off offset:1024
	global_load_dword v6, v[96:97], off offset:2048
	global_load_dword v4, v[96:97], off offset:3072
	global_load_dword v56, v[98:99], off
	global_load_dword v58, v[98:99], off offset:1024
	global_load_dword v60, v[98:99], off offset:2048
	global_load_dword v62, v[98:99], off offset:3072
	global_load_dword v64, v[100:101], off
	global_load_dword v66, v[100:101], off offset:1024
	global_load_dword v68, v[100:101], off offset:2048
	global_load_dword v70, v[100:101], off offset:3072
	global_load_dword v72, v[102:103], off
	global_load_dword v74, v[102:103], off offset:1024
	global_load_dword v76, v[102:103], off offset:2048
	global_load_dword v78, v[102:103], off offset:3072
	global_load_dword v80, v[104:105], off
	global_load_dword v82, v[104:105], off offset:1024
	global_load_dword v84, v[104:105], off offset:2048
	global_load_dword v88, v[104:105], off offset:3072
; __device__ __forceinline__ float bf2f(unsigned short b) { return __uint_as_float(((unsigned)b) << 16); }
; template <int M> __device__ __forceinline__ float shx(float v) { return __builtin_bit_cast(float, __builtin_amdgcn_ds_swizzle(__builtin_bit_cast(int, v), (M << 10) | 0x1f)); }
; __device__ __forceinline__ float sum32(float v) { return v + xhalf(v); }
; __device__ __forceinline__ float wave_sum(float v) {
;   v += shx<16>(v); v += shx<8>(v); v += shx<4>(v); v += shx<2>(v); v += shx<1>(v); return sum32(v);
; }
; __device__ __forceinline__ void up_phase(const bf16_t* cqkv, const bf16_t* wqb, const bf16_t* wkvb, EpiUp& epi) {
;     ...
;     for (int r0 = 0; r0 < 32; r0 += 16) {
;       u32x2 wv[16];
; #pragma unroll
;       for (int rr = 0; rr < 16; ++rr) { if (isq) wv[rr] = *(const u32x2*)(rp + (size_t)(r0 + rr) * 512); else { wv[rr].x = *(const unsigned*)(rp + (size_t)(r0 + rr) * 512); wv[rr].y = 0u; } }
; #pragma unroll
;       for (int rr = 0; rr < 16; ++rr) {
;         const float a = bf2f(wv[rr].x & 0xffff), b = bf2f(wv[rr].x >> 16), c = bf2f(wv[rr].y & 0xffff), d = bf2f(wv[rr].y >> 16);
;         const float ss = wave_sum(a * a + b * b + c * c + d * d);
;         if (lane == 0) rsb[wid * 32 + r0 + rr] = rsqrtf(ss * (isq ? 1.0f / 256.0f : 1.0f / 128.0f) + 1e-6f);
.Lup_ldone:
	s_waitcnt vmcnt(16)
	v_lshlrev_b32_e32 v36, 16, v32
	v_and_b32_e32 v32, 0xffff0000, v32
	v_mul_f32_e32 v32, v32, v32
	v_lshlrev_b32_e32 v37, 16, v33
	v_fmac_f32_e32 v32, v36, v36
	v_and_b32_e32 v33, 0xffff0000, v33
	v_fmac_f32_e32 v32, v37, v37
	v_fmac_f32_e32 v32, v33, v33
	v_lshlrev_b32_e32 v36, 16, v34
	v_and_b32_e32 v34, 0xffff0000, v34
	v_mul_f32_e32 v34, v34, v34
	v_lshlrev_b32_e32 v37, 16, v35
	v_fmac_f32_e32 v34, v36, v36
	v_and_b32_e32 v35, 0xffff0000, v35
	v_fmac_f32_e32 v34, v37, v37
	v_fmac_f32_e32 v34, v35, v35
	v_lshlrev_b32_e32 v36, 16, v30
	v_and_b32_e32 v30, 0xffff0000, v30
	v_mul_f32_e32 v30, v30, v30
	v_lshlrev_b32_e32 v37, 16, v31
	v_fmac_f32_e32 v30, v36, v36
	v_and_b32_e32 v31, 0xffff0000, v31
	v_fmac_f32_e32 v30, v37, v37
	v_fmac_f32_e32 v30, v31, v31
	v_lshlrev_b32_e32 v36, 16, v28
	v_and_b32_e32 v28, 0xffff0000, v28
	v_mul_f32_e32 v28, v28, v28
	v_lshlrev_b32_e32 v37, 16, v29
	v_fmac_f32_e32 v28, v36, v36
	v_and_b32_e32 v29, 0xffff0000, v29
	v_fmac_f32_e32 v28, v37, v37
	v_fmac_f32_e32 v28, v29, v29
	v_lshlrev_b32_e32 v36, 16, v26
	v_and_b32_e32 v26, 0xffff0000, v26
	v_mul_f32_e32 v26, v26, v26
	v_lshlrev_b32_e32 v37, 16, v27
	v_fmac_f32_e32 v26, v36, v36
	v_and_b32_e32 v27, 0xffff0000, v27
	v_fmac_f32_e32 v26, v37, v37
	v_fmac_f32_e32 v26, v27, v27
	v_lshlrev_b32_e32 v36, 16, v24
	v_and_b32_e32 v24, 0xffff0000, v24
	v_mul_f32_e32 v24, v24, v24
	v_lshlrev_b32_e32 v37, 16, v25
	v_fmac_f32_e32 v24, v36, v36
	v_and_b32_e32 v25, 0xffff0000, v25
	v_fmac_f32_e32 v24, v37, v37
	v_fmac_f32_e32 v24, v25, v25
	v_lshlrev_b32_e32 v36, 16, v22
	v_and_b32_e32 v22, 0xffff0000, v22
	v_mul_f32_e32 v22, v22, v22
	v_lshlrev_b32_e32 v37, 16, v23
	v_fmac_f32_e32 v22, v36, v36
	v_and_b32_e32 v23, 0xffff0000, v23
	v_fmac_f32_e32 v22, v37, v37
	v_fmac_f32_e32 v22, v23, v23
	v_lshlrev_b32_e32 v36, 16, v20
	v_and_b32_e32 v20, 0xffff0000, v20
	v_mul_f32_e32 v20, v20, v20
	v_lshlrev_b32_e32 v37, 16, v21
	v_fmac_f32_e32 v20, v36, v36
	v_and_b32_e32 v21, 0xffff0000, v21
	v_fmac_f32_e32 v20, v37, v37
	v_fmac_f32_e32 v20, v21, v21
	v_lshlrev_b32_e32 v36, 16, v18
	v_and_b32_e32 v18, 0xffff0000, v18
	v_mul_f32_e32 v18, v18, v18
	v_lshlrev_b32_e32 v37, 16, v19
	v_fmac_f32_e32 v18, v36, v36
	v_and_b32_e32 v19, 0xffff0000, v19
	v_fmac_f32_e32 v18, v37, v37
	v_fmac_f32_e32 v18, v19, v19
	v_lshlrev_b32_e32 v36, 16, v16
	v_and_b32_e32 v16, 0xffff0000, v16
	v_mul_f32_e32 v16, v16, v16
	v_lshlrev_b32_e32 v37, 16, v17
	v_fmac_f32_e32 v16, v36, v36
	v_and_b32_e32 v17, 0xffff0000, v17
	v_fmac_f32_e32 v16, v37, v37
	v_fmac_f32_e32 v16, v17, v17
	v_lshlrev_b32_e32 v36, 16, v14
	v_and_b32_e32 v14, 0xffff0000, v14
	v_mul_f32_e32 v14, v14, v14
	v_lshlrev_b32_e32 v37, 16, v15
	v_fmac_f32_e32 v14, v36, v36
	v_and_b32_e32 v15, 0xffff0000, v15
	v_fmac_f32_e32 v14, v37, v37
	v_fmac_f32_e32 v14, v15, v15
	v_lshlrev_b32_e32 v36, 16, v12
	v_and_b32_e32 v12, 0xffff0000, v12
	v_mul_f32_e32 v12, v12, v12
	v_lshlrev_b32_e32 v37, 16, v13
	v_fmac_f32_e32 v12, v36, v36
	v_and_b32_e32 v13, 0xffff0000, v13
	v_fmac_f32_e32 v12, v37, v37
	v_fmac_f32_e32 v12, v13, v13
	v_lshlrev_b32_e32 v36, 16, v10
	v_and_b32_e32 v10, 0xffff0000, v10
	v_mul_f32_e32 v10, v10, v10
	v_lshlrev_b32_e32 v37, 16, v11
	v_fmac_f32_e32 v10, v36, v36
	v_and_b32_e32 v11, 0xffff0000, v11
	v_fmac_f32_e32 v10, v37, v37
	v_fmac_f32_e32 v10, v11, v11
	v_lshlrev_b32_e32 v36, 16, v8
	v_and_b32_e32 v8, 0xffff0000, v8
	v_mul_f32_e32 v8, v8, v8
	v_lshlrev_b32_e32 v37, 16, v9
	v_fmac_f32_e32 v8, v36, v36
	v_and_b32_e32 v9, 0xffff0000, v9
	v_fmac_f32_e32 v8, v37, v37
	v_fmac_f32_e32 v8, v9, v9
	v_lshlrev_b32_e32 v36, 16, v6
	v_and_b32_e32 v6, 0xffff0000, v6
	v_mul_f32_e32 v6, v6, v6
	v_lshlrev_b32_e32 v37, 16, v7
	v_fmac_f32_e32 v6, v36, v36
	v_and_b32_e32 v7, 0xffff0000, v7
	v_fmac_f32_e32 v6, v37, v37
	v_fmac_f32_e32 v6, v7, v7
	v_lshlrev_b32_e32 v36, 16, v4
	v_and_b32_e32 v4, 0xffff0000, v4
	v_mul_f32_e32 v4, v4, v4
	v_lshlrev_b32_e32 v37, 16, v5
	v_fmac_f32_e32 v4, v36, v36
	v_and_b32_e32 v5, 0xffff0000, v5
	v_fmac_f32_e32 v4, v37, v37
	v_fmac_f32_e32 v4, v5, v5
	v_lshlrev_b32_e32 v37, 2, v210
	v_xor_b32_e32 v37, 0x80, v37
	ds_swizzle_b32 v33, v32 offset:swizzle(SWAP,16)
	ds_swizzle_b32 v35, v34 offset:swizzle(SWAP,16)
	ds_swizzle_b32 v31, v30 offset:swizzle(SWAP,16)
	ds_swizzle_b32 v29, v28 offset:swizzle(SWAP,16)
	ds_swizzle_b32 v27, v26 offset:swizzle(SWAP,16)
	ds_swizzle_b32 v25, v24 offset:swizzle(SWAP,16)
	ds_swizzle_b32 v23, v22 offset:swizzle(SWAP,16)
	ds_swizzle_b32 v21, v20 offset:swizzle(SWAP,16)
	s_waitcnt lgkmcnt(0)
	v_add_f32_e32 v32, v32, v33
	v_add_f32_e32 v34, v34, v35
	v_add_f32_e32 v30, v30, v31
	v_add_f32_e32 v28, v28, v29
	v_add_f32_e32 v26, v26, v27
	v_add_f32_e32 v24, v24, v25
	v_add_f32_e32 v22, v22, v23
	v_add_f32_e32 v20, v20, v21
	ds_swizzle_b32 v33, v32 offset:swizzle(SWAP,8)
	ds_swizzle_b32 v35, v34 offset:swizzle(SWAP,8)
	ds_swizzle_b32 v31, v30 offset:swizzle(SWAP,8)
	ds_swizzle_b32 v29, v28 offset:swizzle(SWAP,8)
	ds_swizzle_b32 v27, v26 offset:swizzle(SWAP,8)
	ds_swizzle_b32 v25, v24 offset:swizzle(SWAP,8)
	ds_swizzle_b32 v23, v22 offset:swizzle(SWAP,8)
	ds_swizzle_b32 v21, v20 offset:swizzle(SWAP,8)
	s_waitcnt lgkmcnt(0)
	v_add_f32_e32 v32, v32, v33
	v_add_f32_e32 v34, v34, v35
	v_add_f32_e32 v30, v30, v31
	v_add_f32_e32 v28, v28, v29
	v_add_f32_e32 v26, v26, v27
	v_add_f32_e32 v24, v24, v25
	v_add_f32_e32 v22, v22, v23
	v_add_f32_e32 v20, v20, v21
	ds_swizzle_b32 v33, v32 offset:swizzle(SWAP,4)
	ds_swizzle_b32 v35, v34 offset:swizzle(SWAP,4)
	ds_swizzle_b32 v31, v30 offset:swizzle(SWAP,4)
	ds_swizzle_b32 v29, v28 offset:swizzle(SWAP,4)
	ds_swizzle_b32 v27, v26 offset:swizzle(SWAP,4)
	ds_swizzle_b32 v25, v24 offset:swizzle(SWAP,4)
	ds_swizzle_b32 v23, v22 offset:swizzle(SWAP,4)
	ds_swizzle_b32 v21, v20 offset:swizzle(SWAP,4)
	s_waitcnt lgkmcnt(0)
; __device__ __forceinline__ float bf2f(unsigned short b) { return __uint_as_float(((unsigned)b) << 16); }
; template <int M> __device__ __forceinline__ float shx(float v) { return __builtin_bit_cast(float, __builtin_amdgcn_ds_swizzle(__builtin_bit_cast(int, v), (M << 10) | 0x1f)); }
; __device__ __forceinline__ float sum32(float v) { return v + xhalf(v); }
; __device__ __forceinline__ float wave_sum(float v) {
;   v += shx<16>(v); v += shx<8>(v); v += shx<4>(v); v += shx<2>(v); v += shx<1>(v); return sum32(v);
; }
; __device__ __forceinline__ void up_phase(const bf16_t* cqkv, const bf16_t* wqb, const bf16_t* wkvb, EpiUp& epi) {
;     ...
;     for (int r0 = 0; r0 < 32; r0 += 16) {
;       u32x2 wv[16];
; #pragma unroll
;       for (int rr = 0; rr < 16; ++rr) { if (isq) wv[rr] = *(const u32x2*)(rp + (size_t)(r0 + rr) * 512); else { wv[rr].x = *(const unsigned*)(rp + (size_t)(r0 + rr) * 512); wv[rr].y = 0u; } }
; #pragma unroll
;       for (int rr = 0; rr < 16; ++rr) {
;         const float a = bf2f(wv[rr].x & 0xffff), b = bf2f(wv[rr].x >> 16), c = bf2f(wv[rr].y & 0xffff), d = bf2f(wv[rr].y >> 16);
;         const float ss = wave_sum(a * a + b * b + c * c + d * d);
;         if (lane == 0) rsb[wid * 32 + r0 + rr] = rsqrtf(ss * (isq ? 1.0f / 256.0f : 1.0f / 128.0f) + 1e-6f);
	v_add_f32_e32 v32, v32, v33
	v_add_f32_e32 v34, v34, v35
	v_add_f32_e32 v30, v30, v31
	v_add_f32_e32 v28, v28, v29
	v_add_f32_e32 v26, v26, v27
	v_add_f32_e32 v24, v24, v25
	v_add_f32_e32 v22, v22, v23
	v_add_f32_e32 v20, v20, v21
	ds_swizzle_b32 v33, v32 offset:swizzle(SWAP,2)
	ds_swizzle_b32 v35, v34 offset:swizzle(SWAP,2)
	ds_swizzle_b32 v31, v30 offset:swizzle(SWAP,2)
	ds_swizzle_b32 v29, v28 offset:swizzle(SWAP,2)
	ds_swizzle_b32 v27, v26 offset:swizzle(SWAP,2)
	ds_swizzle_b32 v25, v24 offset:swizzle(SWAP,2)
	ds_swizzle_b32 v23, v22 offset:swizzle(SWAP,2)
	ds_swizzle_b32 v21, v20 offset:swizzle(SWAP,2)
	s_waitcnt lgkmcnt(0)
	v_add_f32_e32 v32, v32, v33
	v_add_f32_e32 v34, v34, v35
	v_add_f32_e32 v30, v30, v31
	v_add_f32_e32 v28, v28, v29
	v_add_f32_e32 v26, v26, v27
	v_add_f32_e32 v24, v24, v25
	v_add_f32_e32 v22, v22, v23
	v_add_f32_e32 v20, v20, v21
	ds_swizzle_b32 v33, v32 offset:swizzle(SWAP,1)
	ds_swizzle_b32 v35, v34 offset:swizzle(SWAP,1)
	ds_swizzle_b32 v31, v30 offset:swizzle(SWAP,1)
	ds_swizzle_b32 v29, v28 offset:swizzle(SWAP,1)
	ds_swizzle_b32 v27, v26 offset:swizzle(SWAP,1)
	ds_swizzle_b32 v25, v24 offset:swizzle(SWAP,1)
	ds_swizzle_b32 v23, v22 offset:swizzle(SWAP,1)
	ds_swizzle_b32 v21, v20 offset:swizzle(SWAP,1)
	s_waitcnt lgkmcnt(0)
	v_add_f32_e32 v32, v32, v33
	v_add_f32_e32 v34, v34, v35
	v_add_f32_e32 v30, v30, v31
	v_add_f32_e32 v28, v28, v29
	v_add_f32_e32 v26, v26, v27
	v_add_f32_e32 v24, v24, v25
	v_add_f32_e32 v22, v22, v23
	v_add_f32_e32 v20, v20, v21
	ds_bpermute_b32 v33, v37, v32
	ds_bpermute_b32 v35, v37, v34
	ds_bpermute_b32 v31, v37, v30
	ds_bpermute_b32 v29, v37, v28
	ds_bpermute_b32 v27, v37, v26
	ds_bpermute_b32 v25, v37, v24
	ds_bpermute_b32 v23, v37, v22
	ds_bpermute_b32 v21, v37, v20
	s_waitcnt lgkmcnt(0)
	v_add_f32_e32 v32, v32, v33
	v_add_f32_e32 v34, v34, v35
	v_add_f32_e32 v30, v30, v31
	v_add_f32_e32 v28, v28, v29
	v_add_f32_e32 v26, v26, v27
	v_add_f32_e32 v24, v24, v25
	v_add_f32_e32 v22, v22, v23
	v_add_f32_e32 v20, v20, v21
	ds_swizzle_b32 v19, v18 offset:swizzle(SWAP,16)
	ds_swizzle_b32 v17, v16 offset:swizzle(SWAP,16)
	ds_swizzle_b32 v15, v14 offset:swizzle(SWAP,16)
	ds_swizzle_b32 v13, v12 offset:swizzle(SWAP,16)
	ds_swizzle_b32 v11, v10 offset:swizzle(SWAP,16)
	ds_swizzle_b32 v9, v8 offset:swizzle(SWAP,16)
	ds_swizzle_b32 v7, v6 offset:swizzle(SWAP,16)
	ds_swizzle_b32 v5, v4 offset:swizzle(SWAP,16)
	s_waitcnt lgkmcnt(0)
	v_add_f32_e32 v18, v18, v19
	v_add_f32_e32 v16, v16, v17
	v_add_f32_e32 v14, v14, v15
	v_add_f32_e32 v12, v12, v13
	v_add_f32_e32 v10, v10, v11
	v_add_f32_e32 v8, v8, v9
	v_add_f32_e32 v6, v6, v7
	v_add_f32_e32 v4, v4, v5
	ds_swizzle_b32 v19, v18 offset:swizzle(SWAP,8)
	ds_swizzle_b32 v17, v16 offset:swizzle(SWAP,8)
	ds_swizzle_b32 v15, v14 offset:swizzle(SWAP,8)
	ds_swizzle_b32 v13, v12 offset:swizzle(SWAP,8)
	ds_swizzle_b32 v11, v10 offset:swizzle(SWAP,8)
	ds_swizzle_b32 v9, v8 offset:swizzle(SWAP,8)
	ds_swizzle_b32 v7, v6 offset:swizzle(SWAP,8)
	ds_swizzle_b32 v5, v4 offset:swizzle(SWAP,8)
	s_waitcnt lgkmcnt(0)
	v_add_f32_e32 v18, v18, v19
	v_add_f32_e32 v16, v16, v17
	v_add_f32_e32 v14, v14, v15
	v_add_f32_e32 v12, v12, v13
	v_add_f32_e32 v10, v10, v11
	v_add_f32_e32 v8, v8, v9
	v_add_f32_e32 v6, v6, v7
	v_add_f32_e32 v4, v4, v5
	ds_swizzle_b32 v19, v18 offset:swizzle(SWAP,4)
	ds_swizzle_b32 v17, v16 offset:swizzle(SWAP,4)
	ds_swizzle_b32 v15, v14 offset:swizzle(SWAP,4)
	ds_swizzle_b32 v13, v12 offset:swizzle(SWAP,4)
	ds_swizzle_b32 v11, v10 offset:swizzle(SWAP,4)
	ds_swizzle_b32 v9, v8 offset:swizzle(SWAP,4)
	ds_swizzle_b32 v7, v6 offset:swizzle(SWAP,4)
	ds_swizzle_b32 v5, v4 offset:swizzle(SWAP,4)
	s_waitcnt lgkmcnt(0)
	v_add_f32_e32 v18, v18, v19
	v_add_f32_e32 v16, v16, v17
	v_add_f32_e32 v14, v14, v15
	v_add_f32_e32 v12, v12, v13
	v_add_f32_e32 v10, v10, v11
	v_add_f32_e32 v8, v8, v9
	v_add_f32_e32 v6, v6, v7
	v_add_f32_e32 v4, v4, v5
	ds_swizzle_b32 v19, v18 offset:swizzle(SWAP,2)
	ds_swizzle_b32 v17, v16 offset:swizzle(SWAP,2)
	ds_swizzle_b32 v15, v14 offset:swizzle(SWAP,2)
	ds_swizzle_b32 v13, v12 offset:swizzle(SWAP,2)
	ds_swizzle_b32 v11, v10 offset:swizzle(SWAP,2)
	ds_swizzle_b32 v9, v8 offset:swizzle(SWAP,2)
	ds_swizzle_b32 v7, v6 offset:swizzle(SWAP,2)
	ds_swizzle_b32 v5, v4 offset:swizzle(SWAP,2)
	s_waitcnt lgkmcnt(0)
	v_add_f32_e32 v18, v18, v19
	v_add_f32_e32 v16, v16, v17
	v_add_f32_e32 v14, v14, v15
	v_add_f32_e32 v12, v12, v13
	v_add_f32_e32 v10, v10, v11
	v_add_f32_e32 v8, v8, v9
	v_add_f32_e32 v6, v6, v7
	v_add_f32_e32 v4, v4, v5
	ds_swizzle_b32 v19, v18 offset:swizzle(SWAP,1)
	ds_swizzle_b32 v17, v16 offset:swizzle(SWAP,1)
	ds_swizzle_b32 v15, v14 offset:swizzle(SWAP,1)
	ds_swizzle_b32 v13, v12 offset:swizzle(SWAP,1)
	ds_swizzle_b32 v11, v10 offset:swizzle(SWAP,1)
	ds_swizzle_b32 v9, v8 offset:swizzle(SWAP,1)
	ds_swizzle_b32 v7, v6 offset:swizzle(SWAP,1)
	ds_swizzle_b32 v5, v4 offset:swizzle(SWAP,1)
	s_waitcnt lgkmcnt(0)
	v_add_f32_e32 v18, v18, v19
	v_add_f32_e32 v16, v16, v17
	v_add_f32_e32 v14, v14, v15
	v_add_f32_e32 v12, v12, v13
	v_add_f32_e32 v10, v10, v11
	v_add_f32_e32 v8, v8, v9
	v_add_f32_e32 v6, v6, v7
	v_add_f32_e32 v4, v4, v5
	ds_bpermute_b32 v19, v37, v18
	ds_bpermute_b32 v17, v37, v16
	ds_bpermute_b32 v15, v37, v14
	ds_bpermute_b32 v13, v37, v12
	ds_bpermute_b32 v11, v37, v10
	ds_bpermute_b32 v9, v37, v8
	ds_bpermute_b32 v7, v37, v6
	ds_bpermute_b32 v5, v37, v4
	s_waitcnt lgkmcnt(0)
	v_add_f32_e32 v18, v18, v19
	v_add_f32_e32 v16, v16, v17
	v_add_f32_e32 v14, v14, v15
	v_add_f32_e32 v12, v12, v13
	v_add_f32_e32 v10, v10, v11
	v_add_f32_e32 v8, v8, v9
	v_add_f32_e32 v6, v6, v7
	v_add_f32_e32 v4, v4, v5
	v_mov_b32_e32 v36, v143
	s_and_saveexec_b64 s[4:5], s[2:3]
	s_cbranch_execz .Lup_skipA
; __device__ __forceinline__ float bf2f(unsigned short b) { return __uint_as_float(((unsigned)b) << 16); }
; __device__ __forceinline__ void up_phase(const bf16_t* cqkv, const bf16_t* wqb, const bf16_t* wkvb, EpiUp& epi) {
;     ...
;       for (int rr = 0; rr < 16; ++rr) {
;         const float a = bf2f(wv[rr].x & 0xffff), b = bf2f(wv[rr].x >> 16), c = bf2f(wv[rr].y & 0xffff), d = bf2f(wv[rr].y >> 16);
;         const float ss = wave_sum(a * a + b * b + c * c + d * d);
;         if (lane == 0) rsb[wid * 32 + r0 + rr] = rsqrtf(ss * (isq ? 1.0f / 256.0f : 1.0f / 128.0f) + 1e-6f);
	v_fmaak_f32 v32, v0, v32, 0x358637bd
	v_mul_f32_e32 v33, 0x4b800000, v32
	v_cmp_gt_f32_e32 vcc, s46, v32
	s_nop 1
	v_cndmask_b32_e32 v32, v32, v33, vcc
	v_rsq_f32_e32 v32, v32
	s_nop 0
	v_mul_f32_e32 v33, 0x45800000, v32
	v_cndmask_b32_e32 v32, v32, v33, vcc
	ds_write_b32 v36, v32
	v_fmaak_f32 v34, v0, v34, 0x358637bd
	v_mul_f32_e32 v35, 0x4b800000, v34
	v_cmp_gt_f32_e32 vcc, s46, v34
	s_nop 1
	v_cndmask_b32_e32 v34, v34, v35, vcc
	v_rsq_f32_e32 v34, v34
	s_nop 0
	v_mul_f32_e32 v35, 0x45800000, v34
	v_cndmask_b32_e32 v34, v34, v35, vcc
	ds_write_b32 v36, v34 offset:4
	v_fmaak_f32 v30, v0, v30, 0x358637bd
	v_mul_f32_e32 v31, 0x4b800000, v30
	v_cmp_gt_f32_e32 vcc, s46, v30
	s_nop 1
	v_cndmask_b32_e32 v30, v30, v31, vcc
	v_rsq_f32_e32 v30, v30
	s_nop 0
	v_mul_f32_e32 v31, 0x45800000, v30
	v_cndmask_b32_e32 v30, v30, v31, vcc
	ds_write_b32 v36, v30 offset:8
	v_fmaak_f32 v28, v0, v28, 0x358637bd
	v_mul_f32_e32 v29, 0x4b800000, v28
	v_cmp_gt_f32_e32 vcc, s46, v28
	s_nop 1
	v_cndmask_b32_e32 v28, v28, v29, vcc
	v_rsq_f32_e32 v28, v28
	s_nop 0
	v_mul_f32_e32 v29, 0x45800000, v28
	v_cndmask_b32_e32 v28, v28, v29, vcc
	ds_write_b32 v36, v28 offset:12
	v_fmaak_f32 v26, v0, v26, 0x358637bd
	v_mul_f32_e32 v27, 0x4b800000, v26
	v_cmp_gt_f32_e32 vcc, s46, v26
	s_nop 1
	v_cndmask_b32_e32 v26, v26, v27, vcc
	v_rsq_f32_e32 v26, v26
	s_nop 0
	v_mul_f32_e32 v27, 0x45800000, v26
	v_cndmask_b32_e32 v26, v26, v27, vcc
	ds_write_b32 v36, v26 offset:16
	v_fmaak_f32 v24, v0, v24, 0x358637bd
	v_mul_f32_e32 v25, 0x4b800000, v24
	v_cmp_gt_f32_e32 vcc, s46, v24
	s_nop 1
	v_cndmask_b32_e32 v24, v24, v25, vcc
	v_rsq_f32_e32 v24, v24
	s_nop 0
	v_mul_f32_e32 v25, 0x45800000, v24
	v_cndmask_b32_e32 v24, v24, v25, vcc
	ds_write_b32 v36, v24 offset:20
	v_fmaak_f32 v22, v0, v22, 0x358637bd
	v_mul_f32_e32 v23, 0x4b800000, v22
	v_cmp_gt_f32_e32 vcc, s46, v22
	s_nop 1
	v_cndmask_b32_e32 v22, v22, v23, vcc
	v_rsq_f32_e32 v22, v22
	s_nop 0
	v_mul_f32_e32 v23, 0x45800000, v22
	v_cndmask_b32_e32 v22, v22, v23, vcc
	ds_write_b32 v36, v22 offset:24
	v_fmaak_f32 v20, v0, v20, 0x358637bd
	v_mul_f32_e32 v21, 0x4b800000, v20
	v_cmp_gt_f32_e32 vcc, s46, v20
	s_nop 1
	v_cndmask_b32_e32 v20, v20, v21, vcc
	v_rsq_f32_e32 v20, v20
	s_nop 0
	v_mul_f32_e32 v21, 0x45800000, v20
	v_cndmask_b32_e32 v20, v20, v21, vcc
	ds_write_b32 v36, v20 offset:28
	v_fmaak_f32 v18, v0, v18, 0x358637bd
	v_mul_f32_e32 v19, 0x4b800000, v18
	v_cmp_gt_f32_e32 vcc, s46, v18
	s_nop 1
	v_cndmask_b32_e32 v18, v18, v19, vcc
	v_rsq_f32_e32 v18, v18
	s_nop 0
	v_mul_f32_e32 v19, 0x45800000, v18
	v_cndmask_b32_e32 v18, v18, v19, vcc
	ds_write_b32 v36, v18 offset:32
	v_fmaak_f32 v16, v0, v16, 0x358637bd
	v_mul_f32_e32 v17, 0x4b800000, v16
	v_cmp_gt_f32_e32 vcc, s46, v16
	s_nop 1
	v_cndmask_b32_e32 v16, v16, v17, vcc
	v_rsq_f32_e32 v16, v16
	s_nop 0
	v_mul_f32_e32 v17, 0x45800000, v16
	v_cndmask_b32_e32 v16, v16, v17, vcc
	ds_write_b32 v36, v16 offset:36
	v_fmaak_f32 v14, v0, v14, 0x358637bd
	v_mul_f32_e32 v15, 0x4b800000, v14
	v_cmp_gt_f32_e32 vcc, s46, v14
	s_nop 1
	v_cndmask_b32_e32 v14, v14, v15, vcc
	v_rsq_f32_e32 v14, v14
	s_nop 0
	v_mul_f32_e32 v15, 0x45800000, v14
	v_cndmask_b32_e32 v14, v14, v15, vcc
	ds_write_b32 v36, v14 offset:40
	v_fmaak_f32 v12, v0, v12, 0x358637bd
	v_mul_f32_e32 v13, 0x4b800000, v12
	v_cmp_gt_f32_e32 vcc, s46, v12
	s_nop 1
	v_cndmask_b32_e32 v12, v12, v13, vcc
	v_rsq_f32_e32 v12, v12
	s_nop 0
	v_mul_f32_e32 v13, 0x45800000, v12
	v_cndmask_b32_e32 v12, v12, v13, vcc
	ds_write_b32 v36, v12 offset:44
	v_fmaak_f32 v10, v0, v10, 0x358637bd
	v_mul_f32_e32 v11, 0x4b800000, v10
	v_cmp_gt_f32_e32 vcc, s46, v10
	s_nop 1
	v_cndmask_b32_e32 v10, v10, v11, vcc
	v_rsq_f32_e32 v10, v10
	s_nop 0
	v_mul_f32_e32 v11, 0x45800000, v10
	v_cndmask_b32_e32 v10, v10, v11, vcc
	ds_write_b32 v36, v10 offset:48
	v_fmaak_f32 v8, v0, v8, 0x358637bd
	v_mul_f32_e32 v9, 0x4b800000, v8
	v_cmp_gt_f32_e32 vcc, s46, v8
	s_nop 1
	v_cndmask_b32_e32 v8, v8, v9, vcc
	v_rsq_f32_e32 v8, v8
	s_nop 0
	v_mul_f32_e32 v9, 0x45800000, v8
	v_cndmask_b32_e32 v8, v8, v9, vcc
	ds_write_b32 v36, v8 offset:52
	v_fmaak_f32 v6, v0, v6, 0x358637bd
	v_mul_f32_e32 v7, 0x4b800000, v6
	v_cmp_gt_f32_e32 vcc, s46, v6
	s_nop 1
	v_cndmask_b32_e32 v6, v6, v7, vcc
	v_rsq_f32_e32 v6, v6
	s_nop 0
	v_mul_f32_e32 v7, 0x45800000, v6
	v_cndmask_b32_e32 v6, v6, v7, vcc
	ds_write_b32 v36, v6 offset:56
	v_fmaak_f32 v4, v0, v4, 0x358637bd
	v_mul_f32_e32 v5, 0x4b800000, v4
	v_cmp_gt_f32_e32 vcc, s46, v4
	s_nop 1
	v_cndmask_b32_e32 v4, v4, v5, vcc
	v_rsq_f32_e32 v4, v4
	s_nop 0
	v_mul_f32_e32 v5, 0x45800000, v4
	v_cndmask_b32_e32 v4, v4, v5, vcc
	ds_write_b32 v36, v4 offset:60
; __device__ __forceinline__ float bf2f(unsigned short b) { return __uint_as_float(((unsigned)b) << 16); }
; template <int M> __device__ __forceinline__ float shx(float v) { return __builtin_bit_cast(float, __builtin_amdgcn_ds_swizzle(__builtin_bit_cast(int, v), (M << 10) | 0x1f)); }
; __device__ __forceinline__ float sum32(float v) { return v + xhalf(v); }
; __device__ __forceinline__ float wave_sum(float v) {
;   v += shx<16>(v); v += shx<8>(v); v += shx<4>(v); v += shx<2>(v); v += shx<1>(v); return sum32(v);
; }
; __device__ __forceinline__ void up_phase(const bf16_t* cqkv, const bf16_t* wqb, const bf16_t* wkvb, EpiUp& epi) {
;     ...
;     for (int r0 = 0; r0 < 32; r0 += 16) {
;       u32x2 wv[16];
; #pragma unroll
;       for (int rr = 0; rr < 16; ++rr) { if (isq) wv[rr] = *(const u32x2*)(rp + (size_t)(r0 + rr) * 512); else { wv[rr].x = *(const unsigned*)(rp + (size_t)(r0 + rr) * 512); wv[rr].y = 0u; } }
; #pragma unroll
;       for (int rr = 0; rr < 16; ++rr) {
;         const float a = bf2f(wv[rr].x & 0xffff), b = bf2f(wv[rr].x >> 16), c = bf2f(wv[rr].y & 0xffff), d = bf2f(wv[rr].y >> 16);
;         const float ss = wave_sum(a * a + b * b + c * c + d * d);
.Lup_skipA:
	s_or_b64 exec, exec, s[4:5]
	s_waitcnt vmcnt(0)
	v_lshlrev_b32_e32 v90, 16, v56
	v_and_b32_e32 v56, 0xffff0000, v56
	v_mul_f32_e32 v56, v56, v56
	v_lshlrev_b32_e32 v91, 16, v57
	v_fmac_f32_e32 v56, v90, v90
	v_and_b32_e32 v57, 0xffff0000, v57
	v_fmac_f32_e32 v56, v91, v91
	v_fmac_f32_e32 v56, v57, v57
	v_lshlrev_b32_e32 v90, 16, v58
	v_and_b32_e32 v58, 0xffff0000, v58
	v_mul_f32_e32 v58, v58, v58
	v_lshlrev_b32_e32 v91, 16, v59
	v_fmac_f32_e32 v58, v90, v90
	v_and_b32_e32 v59, 0xffff0000, v59
	v_fmac_f32_e32 v58, v91, v91
	v_fmac_f32_e32 v58, v59, v59
	v_lshlrev_b32_e32 v90, 16, v60
	v_and_b32_e32 v60, 0xffff0000, v60
	v_mul_f32_e32 v60, v60, v60
	v_lshlrev_b32_e32 v91, 16, v61
	v_fmac_f32_e32 v60, v90, v90
	v_and_b32_e32 v61, 0xffff0000, v61
	v_fmac_f32_e32 v60, v91, v91
	v_fmac_f32_e32 v60, v61, v61
	v_lshlrev_b32_e32 v90, 16, v62
	v_and_b32_e32 v62, 0xffff0000, v62
	v_mul_f32_e32 v62, v62, v62
	v_lshlrev_b32_e32 v91, 16, v63
	v_fmac_f32_e32 v62, v90, v90
	v_and_b32_e32 v63, 0xffff0000, v63
	v_fmac_f32_e32 v62, v91, v91
	v_fmac_f32_e32 v62, v63, v63
	v_lshlrev_b32_e32 v90, 16, v64
	v_and_b32_e32 v64, 0xffff0000, v64
	v_mul_f32_e32 v64, v64, v64
	v_lshlrev_b32_e32 v91, 16, v65
	v_fmac_f32_e32 v64, v90, v90
	v_and_b32_e32 v65, 0xffff0000, v65
	v_fmac_f32_e32 v64, v91, v91
	v_fmac_f32_e32 v64, v65, v65
	v_lshlrev_b32_e32 v90, 16, v66
	v_and_b32_e32 v66, 0xffff0000, v66
	v_mul_f32_e32 v66, v66, v66
	v_lshlrev_b32_e32 v91, 16, v67
	v_fmac_f32_e32 v66, v90, v90
	v_and_b32_e32 v67, 0xffff0000, v67
	v_fmac_f32_e32 v66, v91, v91
	v_fmac_f32_e32 v66, v67, v67
	v_lshlrev_b32_e32 v90, 16, v68
	v_and_b32_e32 v68, 0xffff0000, v68
	v_mul_f32_e32 v68, v68, v68
	v_lshlrev_b32_e32 v91, 16, v69
	v_fmac_f32_e32 v68, v90, v90
	v_and_b32_e32 v69, 0xffff0000, v69
	v_fmac_f32_e32 v68, v91, v91
	v_fmac_f32_e32 v68, v69, v69
	v_lshlrev_b32_e32 v90, 16, v70
	v_and_b32_e32 v70, 0xffff0000, v70
	v_mul_f32_e32 v70, v70, v70
	v_lshlrev_b32_e32 v91, 16, v71
	v_fmac_f32_e32 v70, v90, v90
	v_and_b32_e32 v71, 0xffff0000, v71
	v_fmac_f32_e32 v70, v91, v91
	v_fmac_f32_e32 v70, v71, v71
	v_lshlrev_b32_e32 v90, 16, v72
	v_and_b32_e32 v72, 0xffff0000, v72
	v_mul_f32_e32 v72, v72, v72
	v_lshlrev_b32_e32 v91, 16, v73
	v_fmac_f32_e32 v72, v90, v90
	v_and_b32_e32 v73, 0xffff0000, v73
	v_fmac_f32_e32 v72, v91, v91
	v_fmac_f32_e32 v72, v73, v73
	v_lshlrev_b32_e32 v90, 16, v74
	v_and_b32_e32 v74, 0xffff0000, v74
	v_mul_f32_e32 v74, v74, v74
	v_lshlrev_b32_e32 v91, 16, v75
	v_fmac_f32_e32 v74, v90, v90
	v_and_b32_e32 v75, 0xffff0000, v75
	v_fmac_f32_e32 v74, v91, v91
	v_fmac_f32_e32 v74, v75, v75
	v_lshlrev_b32_e32 v90, 16, v76
	v_and_b32_e32 v76, 0xffff0000, v76
	v_mul_f32_e32 v76, v76, v76
	v_lshlrev_b32_e32 v91, 16, v77
	v_fmac_f32_e32 v76, v90, v90
	v_and_b32_e32 v77, 0xffff0000, v77
	v_fmac_f32_e32 v76, v91, v91
	v_fmac_f32_e32 v76, v77, v77
	v_lshlrev_b32_e32 v90, 16, v78
	v_and_b32_e32 v78, 0xffff0000, v78
	v_mul_f32_e32 v78, v78, v78
	v_lshlrev_b32_e32 v91, 16, v79
	v_fmac_f32_e32 v78, v90, v90
	v_and_b32_e32 v79, 0xffff0000, v79
	v_fmac_f32_e32 v78, v91, v91
	v_fmac_f32_e32 v78, v79, v79
	v_lshlrev_b32_e32 v90, 16, v80
	v_and_b32_e32 v80, 0xffff0000, v80
	v_mul_f32_e32 v80, v80, v80
	v_lshlrev_b32_e32 v91, 16, v81
	v_fmac_f32_e32 v80, v90, v90
	v_and_b32_e32 v81, 0xffff0000, v81
	v_fmac_f32_e32 v80, v91, v91
	v_fmac_f32_e32 v80, v81, v81
	v_lshlrev_b32_e32 v90, 16, v82
	v_and_b32_e32 v82, 0xffff0000, v82
	v_mul_f32_e32 v82, v82, v82
	v_lshlrev_b32_e32 v91, 16, v83
	v_fmac_f32_e32 v82, v90, v90
	v_and_b32_e32 v83, 0xffff0000, v83
	v_fmac_f32_e32 v82, v91, v91
	v_fmac_f32_e32 v82, v83, v83
	v_lshlrev_b32_e32 v90, 16, v84
	v_and_b32_e32 v84, 0xffff0000, v84
	v_mul_f32_e32 v84, v84, v84
	v_lshlrev_b32_e32 v91, 16, v85
	v_fmac_f32_e32 v84, v90, v90
	v_and_b32_e32 v85, 0xffff0000, v85
	v_fmac_f32_e32 v84, v91, v91
	v_fmac_f32_e32 v84, v85, v85
	v_lshlrev_b32_e32 v90, 16, v88
	v_and_b32_e32 v88, 0xffff0000, v88
	v_mul_f32_e32 v88, v88, v88
	v_lshlrev_b32_e32 v91, 16, v89
	v_fmac_f32_e32 v88, v90, v90
	v_and_b32_e32 v89, 0xffff0000, v89
	v_fmac_f32_e32 v88, v91, v91
	v_fmac_f32_e32 v88, v89, v89
	v_lshlrev_b32_e32 v91, 2, v210
	v_xor_b32_e32 v91, 0x80, v91
	ds_swizzle_b32 v57, v56 offset:swizzle(SWAP,16)
	ds_swizzle_b32 v59, v58 offset:swizzle(SWAP,16)
	ds_swizzle_b32 v61, v60 offset:swizzle(SWAP,16)
	ds_swizzle_b32 v63, v62 offset:swizzle(SWAP,16)
	ds_swizzle_b32 v65, v64 offset:swizzle(SWAP,16)
	ds_swizzle_b32 v67, v66 offset:swizzle(SWAP,16)
	ds_swizzle_b32 v69, v68 offset:swizzle(SWAP,16)
	ds_swizzle_b32 v71, v70 offset:swizzle(SWAP,16)
	s_waitcnt lgkmcnt(0)
	v_add_f32_e32 v56, v56, v57
	v_add_f32_e32 v58, v58, v59
	v_add_f32_e32 v60, v60, v61
	v_add_f32_e32 v62, v62, v63
	v_add_f32_e32 v64, v64, v65
	v_add_f32_e32 v66, v66, v67
	v_add_f32_e32 v68, v68, v69
	v_add_f32_e32 v70, v70, v71
	ds_swizzle_b32 v57, v56 offset:swizzle(SWAP,8)
	ds_swizzle_b32 v59, v58 offset:swizzle(SWAP,8)
	ds_swizzle_b32 v61, v60 offset:swizzle(SWAP,8)
	ds_swizzle_b32 v63, v62 offset:swizzle(SWAP,8)
	ds_swizzle_b32 v65, v64 offset:swizzle(SWAP,8)
	ds_swizzle_b32 v67, v66 offset:swizzle(SWAP,8)
	ds_swizzle_b32 v69, v68 offset:swizzle(SWAP,8)
	ds_swizzle_b32 v71, v70 offset:swizzle(SWAP,8)
	s_waitcnt lgkmcnt(0)
	v_add_f32_e32 v56, v56, v57
	v_add_f32_e32 v58, v58, v59
	v_add_f32_e32 v60, v60, v61
	v_add_f32_e32 v62, v62, v63
	v_add_f32_e32 v64, v64, v65
	v_add_f32_e32 v66, v66, v67
	v_add_f32_e32 v68, v68, v69
	v_add_f32_e32 v70, v70, v71
	ds_swizzle_b32 v57, v56 offset:swizzle(SWAP,4)
	ds_swizzle_b32 v59, v58 offset:swizzle(SWAP,4)
	ds_swizzle_b32 v61, v60 offset:swizzle(SWAP,4)
	ds_swizzle_b32 v63, v62 offset:swizzle(SWAP,4)
	ds_swizzle_b32 v65, v64 offset:swizzle(SWAP,4)
	ds_swizzle_b32 v67, v66 offset:swizzle(SWAP,4)
	ds_swizzle_b32 v69, v68 offset:swizzle(SWAP,4)
	ds_swizzle_b32 v71, v70 offset:swizzle(SWAP,4)
	s_waitcnt lgkmcnt(0)
; __device__ __forceinline__ float bf2f(unsigned short b) { return __uint_as_float(((unsigned)b) << 16); }
; template <int M> __device__ __forceinline__ float shx(float v) { return __builtin_bit_cast(float, __builtin_amdgcn_ds_swizzle(__builtin_bit_cast(int, v), (M << 10) | 0x1f)); }
; __device__ __forceinline__ float sum32(float v) { return v + xhalf(v); }
; __device__ __forceinline__ float wave_sum(float v) {
;   v += shx<16>(v); v += shx<8>(v); v += shx<4>(v); v += shx<2>(v); v += shx<1>(v); return sum32(v);
; }
; __device__ __forceinline__ void up_phase(const bf16_t* cqkv, const bf16_t* wqb, const bf16_t* wkvb, EpiUp& epi) {
;     ...
;     for (int r0 = 0; r0 < 32; r0 += 16) {
;       u32x2 wv[16];
; #pragma unroll
;       for (int rr = 0; rr < 16; ++rr) { if (isq) wv[rr] = *(const u32x2*)(rp + (size_t)(r0 + rr) * 512); else { wv[rr].x = *(const unsigned*)(rp + (size_t)(r0 + rr) * 512); wv[rr].y = 0u; } }
; #pragma unroll
;       for (int rr = 0; rr < 16; ++rr) {
;         const float a = bf2f(wv[rr].x & 0xffff), b = bf2f(wv[rr].x >> 16), c = bf2f(wv[rr].y & 0xffff), d = bf2f(wv[rr].y >> 16);
;         const float ss = wave_sum(a * a + b * b + c * c + d * d);
	v_add_f32_e32 v56, v56, v57
	v_add_f32_e32 v58, v58, v59
	v_add_f32_e32 v60, v60, v61
	v_add_f32_e32 v62, v62, v63
	v_add_f32_e32 v64, v64, v65
	v_add_f32_e32 v66, v66, v67
	v_add_f32_e32 v68, v68, v69
	v_add_f32_e32 v70, v70, v71
	ds_swizzle_b32 v57, v56 offset:swizzle(SWAP,2)
	ds_swizzle_b32 v59, v58 offset:swizzle(SWAP,2)
	ds_swizzle_b32 v61, v60 offset:swizzle(SWAP,2)
	ds_swizzle_b32 v63, v62 offset:swizzle(SWAP,2)
	ds_swizzle_b32 v65, v64 offset:swizzle(SWAP,2)
	ds_swizzle_b32 v67, v66 offset:swizzle(SWAP,2)
	ds_swizzle_b32 v69, v68 offset:swizzle(SWAP,2)
	ds_swizzle_b32 v71, v70 offset:swizzle(SWAP,2)
	s_waitcnt lgkmcnt(0)
	v_add_f32_e32 v56, v56, v57
	v_add_f32_e32 v58, v58, v59
	v_add_f32_e32 v60, v60, v61
	v_add_f32_e32 v62, v62, v63
	v_add_f32_e32 v64, v64, v65
	v_add_f32_e32 v66, v66, v67
	v_add_f32_e32 v68, v68, v69
	v_add_f32_e32 v70, v70, v71
	ds_swizzle_b32 v57, v56 offset:swizzle(SWAP,1)
	ds_swizzle_b32 v59, v58 offset:swizzle(SWAP,1)
	ds_swizzle_b32 v61, v60 offset:swizzle(SWAP,1)
	ds_swizzle_b32 v63, v62 offset:swizzle(SWAP,1)
	ds_swizzle_b32 v65, v64 offset:swizzle(SWAP,1)
	ds_swizzle_b32 v67, v66 offset:swizzle(SWAP,1)
	ds_swizzle_b32 v69, v68 offset:swizzle(SWAP,1)
	ds_swizzle_b32 v71, v70 offset:swizzle(SWAP,1)
	s_waitcnt lgkmcnt(0)
	v_add_f32_e32 v56, v56, v57
	v_add_f32_e32 v58, v58, v59
	v_add_f32_e32 v60, v60, v61
	v_add_f32_e32 v62, v62, v63
	v_add_f32_e32 v64, v64, v65
	v_add_f32_e32 v66, v66, v67
	v_add_f32_e32 v68, v68, v69
	v_add_f32_e32 v70, v70, v71
	ds_bpermute_b32 v57, v91, v56
	ds_bpermute_b32 v59, v91, v58
	ds_bpermute_b32 v61, v91, v60
	ds_bpermute_b32 v63, v91, v62
	ds_bpermute_b32 v65, v91, v64
	ds_bpermute_b32 v67, v91, v66
	ds_bpermute_b32 v69, v91, v68
	ds_bpermute_b32 v71, v91, v70
	s_waitcnt lgkmcnt(0)
	v_add_f32_e32 v56, v56, v57
	v_add_f32_e32 v58, v58, v59
	v_add_f32_e32 v60, v60, v61
	v_add_f32_e32 v62, v62, v63
	v_add_f32_e32 v64, v64, v65
	v_add_f32_e32 v66, v66, v67
	v_add_f32_e32 v68, v68, v69
	v_add_f32_e32 v70, v70, v71
	ds_swizzle_b32 v73, v72 offset:swizzle(SWAP,16)
	ds_swizzle_b32 v75, v74 offset:swizzle(SWAP,16)
	ds_swizzle_b32 v77, v76 offset:swizzle(SWAP,16)
	ds_swizzle_b32 v79, v78 offset:swizzle(SWAP,16)
	ds_swizzle_b32 v81, v80 offset:swizzle(SWAP,16)
	ds_swizzle_b32 v83, v82 offset:swizzle(SWAP,16)
	ds_swizzle_b32 v85, v84 offset:swizzle(SWAP,16)
	ds_swizzle_b32 v89, v88 offset:swizzle(SWAP,16)
	s_waitcnt lgkmcnt(0)
	v_add_f32_e32 v72, v72, v73
	v_add_f32_e32 v74, v74, v75
	v_add_f32_e32 v76, v76, v77
	v_add_f32_e32 v78, v78, v79
	v_add_f32_e32 v80, v80, v81
	v_add_f32_e32 v82, v82, v83
	v_add_f32_e32 v84, v84, v85
	v_add_f32_e32 v88, v88, v89
	ds_swizzle_b32 v73, v72 offset:swizzle(SWAP,8)
	ds_swizzle_b32 v75, v74 offset:swizzle(SWAP,8)
	ds_swizzle_b32 v77, v76 offset:swizzle(SWAP,8)
	ds_swizzle_b32 v79, v78 offset:swizzle(SWAP,8)
	ds_swizzle_b32 v81, v80 offset:swizzle(SWAP,8)
	ds_swizzle_b32 v83, v82 offset:swizzle(SWAP,8)
	ds_swizzle_b32 v85, v84 offset:swizzle(SWAP,8)
	ds_swizzle_b32 v89, v88 offset:swizzle(SWAP,8)
	s_waitcnt lgkmcnt(0)
	v_add_f32_e32 v72, v72, v73
	v_add_f32_e32 v74, v74, v75
	v_add_f32_e32 v76, v76, v77
	v_add_f32_e32 v78, v78, v79
	v_add_f32_e32 v80, v80, v81
	v_add_f32_e32 v82, v82, v83
	v_add_f32_e32 v84, v84, v85
	v_add_f32_e32 v88, v88, v89
	ds_swizzle_b32 v73, v72 offset:swizzle(SWAP,4)
	ds_swizzle_b32 v75, v74 offset:swizzle(SWAP,4)
	ds_swizzle_b32 v77, v76 offset:swizzle(SWAP,4)
	ds_swizzle_b32 v79, v78 offset:swizzle(SWAP,4)
	ds_swizzle_b32 v81, v80 offset:swizzle(SWAP,4)
	ds_swizzle_b32 v83, v82 offset:swizzle(SWAP,4)
	ds_swizzle_b32 v85, v84 offset:swizzle(SWAP,4)
	ds_swizzle_b32 v89, v88 offset:swizzle(SWAP,4)
	s_waitcnt lgkmcnt(0)
	v_add_f32_e32 v72, v72, v73
	v_add_f32_e32 v74, v74, v75
	v_add_f32_e32 v76, v76, v77
	v_add_f32_e32 v78, v78, v79
	v_add_f32_e32 v80, v80, v81
	v_add_f32_e32 v82, v82, v83
	v_add_f32_e32 v84, v84, v85
	v_add_f32_e32 v88, v88, v89
	ds_swizzle_b32 v73, v72 offset:swizzle(SWAP,2)
	ds_swizzle_b32 v75, v74 offset:swizzle(SWAP,2)
	ds_swizzle_b32 v77, v76 offset:swizzle(SWAP,2)
	ds_swizzle_b32 v79, v78 offset:swizzle(SWAP,2)
	ds_swizzle_b32 v81, v80 offset:swizzle(SWAP,2)
	ds_swizzle_b32 v83, v82 offset:swizzle(SWAP,2)
	ds_swizzle_b32 v85, v84 offset:swizzle(SWAP,2)
	ds_swizzle_b32 v89, v88 offset:swizzle(SWAP,2)
	s_waitcnt lgkmcnt(0)
	v_add_f32_e32 v72, v72, v73
	v_add_f32_e32 v74, v74, v75
	v_add_f32_e32 v76, v76, v77
	v_add_f32_e32 v78, v78, v79
	v_add_f32_e32 v80, v80, v81
	v_add_f32_e32 v82, v82, v83
	v_add_f32_e32 v84, v84, v85
	v_add_f32_e32 v88, v88, v89
	ds_swizzle_b32 v73, v72 offset:swizzle(SWAP,1)
	ds_swizzle_b32 v75, v74 offset:swizzle(SWAP,1)
	ds_swizzle_b32 v77, v76 offset:swizzle(SWAP,1)
	ds_swizzle_b32 v79, v78 offset:swizzle(SWAP,1)
	ds_swizzle_b32 v81, v80 offset:swizzle(SWAP,1)
	ds_swizzle_b32 v83, v82 offset:swizzle(SWAP,1)
	ds_swizzle_b32 v85, v84 offset:swizzle(SWAP,1)
	ds_swizzle_b32 v89, v88 offset:swizzle(SWAP,1)
	s_waitcnt lgkmcnt(0)
	v_add_f32_e32 v72, v72, v73
	v_add_f32_e32 v74, v74, v75
	v_add_f32_e32 v76, v76, v77
	v_add_f32_e32 v78, v78, v79
	v_add_f32_e32 v80, v80, v81
	v_add_f32_e32 v82, v82, v83
	v_add_f32_e32 v84, v84, v85
	v_add_f32_e32 v88, v88, v89
	ds_bpermute_b32 v73, v91, v72
	ds_bpermute_b32 v75, v91, v74
	ds_bpermute_b32 v77, v91, v76
	ds_bpermute_b32 v79, v91, v78
	ds_bpermute_b32 v81, v91, v80
	ds_bpermute_b32 v83, v91, v82
	ds_bpermute_b32 v85, v91, v84
	ds_bpermute_b32 v89, v91, v88
	s_waitcnt lgkmcnt(0)
	v_add_f32_e32 v72, v72, v73
	v_add_f32_e32 v74, v74, v75
	v_add_f32_e32 v76, v76, v77
	v_add_f32_e32 v78, v78, v79
	v_add_f32_e32 v80, v80, v81
	v_add_f32_e32 v82, v82, v83
	v_add_f32_e32 v84, v84, v85
	v_add_f32_e32 v88, v88, v89
	v_add_u32_e32 v90, 64, v143
	s_and_saveexec_b64 s[4:5], s[2:3]
	s_cbranch_execz .Lup_skipB
; __device__ __forceinline__ float bf2f(unsigned short b) { return __uint_as_float(((unsigned)b) << 16); }
; __device__ __forceinline__ void up_phase(const bf16_t* cqkv, const bf16_t* wqb, const bf16_t* wkvb, EpiUp& epi) {
;     ...
;       for (int rr = 0; rr < 16; ++rr) {
;         const float a = bf2f(wv[rr].x & 0xffff), b = bf2f(wv[rr].x >> 16), c = bf2f(wv[rr].y & 0xffff), d = bf2f(wv[rr].y >> 16);
;         const float ss = wave_sum(a * a + b * b + c * c + d * d);
;         if (lane == 0) rsb[wid * 32 + r0 + rr] = rsqrtf(ss * (isq ? 1.0f / 256.0f : 1.0f / 128.0f) + 1e-6f);
	v_fmaak_f32 v56, v0, v56, 0x358637bd
	v_mul_f32_e32 v57, 0x4b800000, v56
	v_cmp_gt_f32_e32 vcc, s46, v56
	s_nop 1
	v_cndmask_b32_e32 v56, v56, v57, vcc
	v_rsq_f32_e32 v56, v56
	s_nop 0
	v_mul_f32_e32 v57, 0x45800000, v56
	v_cndmask_b32_e32 v56, v56, v57, vcc
	ds_write_b32 v90, v56
	v_fmaak_f32 v58, v0, v58, 0x358637bd
	v_mul_f32_e32 v59, 0x4b800000, v58
	v_cmp_gt_f32_e32 vcc, s46, v58
	s_nop 1
	v_cndmask_b32_e32 v58, v58, v59, vcc
	v_rsq_f32_e32 v58, v58
	s_nop 0
	v_mul_f32_e32 v59, 0x45800000, v58
	v_cndmask_b32_e32 v58, v58, v59, vcc
	ds_write_b32 v90, v58 offset:4
	v_fmaak_f32 v60, v0, v60, 0x358637bd
	v_mul_f32_e32 v61, 0x4b800000, v60
	v_cmp_gt_f32_e32 vcc, s46, v60
	s_nop 1
	v_cndmask_b32_e32 v60, v60, v61, vcc
	v_rsq_f32_e32 v60, v60
	s_nop 0
	v_mul_f32_e32 v61, 0x45800000, v60
	v_cndmask_b32_e32 v60, v60, v61, vcc
	ds_write_b32 v90, v60 offset:8
	v_fmaak_f32 v62, v0, v62, 0x358637bd
	v_mul_f32_e32 v63, 0x4b800000, v62
	v_cmp_gt_f32_e32 vcc, s46, v62
	s_nop 1
	v_cndmask_b32_e32 v62, v62, v63, vcc
	v_rsq_f32_e32 v62, v62
	s_nop 0
	v_mul_f32_e32 v63, 0x45800000, v62
	v_cndmask_b32_e32 v62, v62, v63, vcc
	ds_write_b32 v90, v62 offset:12
	v_fmaak_f32 v64, v0, v64, 0x358637bd
	v_mul_f32_e32 v65, 0x4b800000, v64
	v_cmp_gt_f32_e32 vcc, s46, v64
	s_nop 1
	v_cndmask_b32_e32 v64, v64, v65, vcc
	v_rsq_f32_e32 v64, v64
	s_nop 0
	v_mul_f32_e32 v65, 0x45800000, v64
	v_cndmask_b32_e32 v64, v64, v65, vcc
	ds_write_b32 v90, v64 offset:16
	v_fmaak_f32 v66, v0, v66, 0x358637bd
	v_mul_f32_e32 v67, 0x4b800000, v66
	v_cmp_gt_f32_e32 vcc, s46, v66
	s_nop 1
	v_cndmask_b32_e32 v66, v66, v67, vcc
	v_rsq_f32_e32 v66, v66
	s_nop 0
	v_mul_f32_e32 v67, 0x45800000, v66
	v_cndmask_b32_e32 v66, v66, v67, vcc
	ds_write_b32 v90, v66 offset:20
	v_fmaak_f32 v68, v0, v68, 0x358637bd
	v_mul_f32_e32 v69, 0x4b800000, v68
	v_cmp_gt_f32_e32 vcc, s46, v68
	s_nop 1
	v_cndmask_b32_e32 v68, v68, v69, vcc
	v_rsq_f32_e32 v68, v68
	s_nop 0
	v_mul_f32_e32 v69, 0x45800000, v68
	v_cndmask_b32_e32 v68, v68, v69, vcc
	ds_write_b32 v90, v68 offset:24
	v_fmaak_f32 v70, v0, v70, 0x358637bd
	v_mul_f32_e32 v71, 0x4b800000, v70
	v_cmp_gt_f32_e32 vcc, s46, v70
	s_nop 1
	v_cndmask_b32_e32 v70, v70, v71, vcc
	v_rsq_f32_e32 v70, v70
	s_nop 0
	v_mul_f32_e32 v71, 0x45800000, v70
	v_cndmask_b32_e32 v70, v70, v71, vcc
	ds_write_b32 v90, v70 offset:28
	v_fmaak_f32 v72, v0, v72, 0x358637bd
	v_mul_f32_e32 v73, 0x4b800000, v72
	v_cmp_gt_f32_e32 vcc, s46, v72
	s_nop 1
	v_cndmask_b32_e32 v72, v72, v73, vcc
	v_rsq_f32_e32 v72, v72
	s_nop 0
	v_mul_f32_e32 v73, 0x45800000, v72
	v_cndmask_b32_e32 v72, v72, v73, vcc
	ds_write_b32 v90, v72 offset:32
	v_fmaak_f32 v74, v0, v74, 0x358637bd
	v_mul_f32_e32 v75, 0x4b800000, v74
	v_cmp_gt_f32_e32 vcc, s46, v74
	s_nop 1
	v_cndmask_b32_e32 v74, v74, v75, vcc
	v_rsq_f32_e32 v74, v74
	s_nop 0
	v_mul_f32_e32 v75, 0x45800000, v74
	v_cndmask_b32_e32 v74, v74, v75, vcc
	ds_write_b32 v90, v74 offset:36
	v_fmaak_f32 v76, v0, v76, 0x358637bd
	v_mul_f32_e32 v77, 0x4b800000, v76
	v_cmp_gt_f32_e32 vcc, s46, v76
	s_nop 1
	v_cndmask_b32_e32 v76, v76, v77, vcc
	v_rsq_f32_e32 v76, v76
	s_nop 0
	v_mul_f32_e32 v77, 0x45800000, v76
	v_cndmask_b32_e32 v76, v76, v77, vcc
	ds_write_b32 v90, v76 offset:40
	v_fmaak_f32 v78, v0, v78, 0x358637bd
	v_mul_f32_e32 v79, 0x4b800000, v78
	v_cmp_gt_f32_e32 vcc, s46, v78
	s_nop 1
	v_cndmask_b32_e32 v78, v78, v79, vcc
	v_rsq_f32_e32 v78, v78
	s_nop 0
	v_mul_f32_e32 v79, 0x45800000, v78
	v_cndmask_b32_e32 v78, v78, v79, vcc
	ds_write_b32 v90, v78 offset:44
	v_fmaak_f32 v80, v0, v80, 0x358637bd
	v_mul_f32_e32 v81, 0x4b800000, v80
	v_cmp_gt_f32_e32 vcc, s46, v80
	s_nop 1
	v_cndmask_b32_e32 v80, v80, v81, vcc
	v_rsq_f32_e32 v80, v80
	s_nop 0
	v_mul_f32_e32 v81, 0x45800000, v80
	v_cndmask_b32_e32 v80, v80, v81, vcc
	ds_write_b32 v90, v80 offset:48
	v_fmaak_f32 v82, v0, v82, 0x358637bd
	v_mul_f32_e32 v83, 0x4b800000, v82
	v_cmp_gt_f32_e32 vcc, s46, v82
	s_nop 1
	v_cndmask_b32_e32 v82, v82, v83, vcc
	v_rsq_f32_e32 v82, v82
	s_nop 0
	v_mul_f32_e32 v83, 0x45800000, v82
	v_cndmask_b32_e32 v82, v82, v83, vcc
	ds_write_b32 v90, v82 offset:52
	v_fmaak_f32 v84, v0, v84, 0x358637bd
	v_mul_f32_e32 v85, 0x4b800000, v84
	v_cmp_gt_f32_e32 vcc, s46, v84
	s_nop 1
	v_cndmask_b32_e32 v84, v84, v85, vcc
	v_rsq_f32_e32 v84, v84
	s_nop 0
	v_mul_f32_e32 v85, 0x45800000, v84
	v_cndmask_b32_e32 v84, v84, v85, vcc
	ds_write_b32 v90, v84 offset:56
	v_fmaak_f32 v88, v0, v88, 0x358637bd
	v_mul_f32_e32 v89, 0x4b800000, v88
	v_cmp_gt_f32_e32 vcc, s46, v88
	s_nop 1
	v_cndmask_b32_e32 v88, v88, v89, vcc
	v_rsq_f32_e32 v88, v88
	s_nop 0
	v_mul_f32_e32 v89, 0x45800000, v88
	v_cndmask_b32_e32 v88, v88, v89, vcc
	ds_write_b32 v90, v88 offset:60
; #define G_STAGE(P, BASE, LD, br, kt) do { const char* _gp = (const char*)((BASE) + (size_t)(br) * (LD) + (size_t)(kt) * BK); \
;     _Pragma("unroll") for (int _i = 0; _i < 2; ++_i)   \
;       __builtin_amdgcn_global_load_lds((const unsigned*)(_gp + (size_t)_i * 128 * (LD) + off_##BASE), (unsigned*)((P) + tid * 16 + _i * 8192), 16, 0, 0); } while (0)
; #define BAR __builtin_amdgcn_s_barrier()
;     ...
;   { int r_, c_; stage_rc(tid * 16, r_, c_); off_A = (unsigned)(r_ * lda + c_) * 2u; off_Bt = (unsigned)(r_ * ldb + c_) * 2u; }
;   if (!prestaged) {
;     G_STAGE(G_SB(0, 0), Bt, ldb, bcol, 0); G_STAGE(G_SA(0, 0), A, lda, brow, 0);
;     G_STAGE(G_SB(0, 1), Bt, ldb, bcol + HALF, 0); G_STAGE(G_SA(0, 1), A, lda, brow + HALF, 0);
;   }
;   if (wr == 1) BAR;
; __device__ __forceinline__ void up_phase(const bf16_t* cqkv, const bf16_t* wqb, const bf16_t* wkvb, EpiUp& epi) {
;     ...
;     epi.brow = brow;
;     if (isq) gemm_tile(cqkv, 512, wqb, 256, 256, brow, pn * BM, epi);
.Lup_skipB:
	s_or_b64 exec, exec, s[4:5]
.LBB0_940:
	s_lshl_b32 s90, s42, 8
	s_mov_b64 s[4:5], -1
	s_and_b64 vcc, exec, s[6:7]
	s_cbranch_vccz .LBB0_1028
	v_mov_b32_e32 v134, v155
	s_add_i32 s8, s90, 0xfffffd00
	v_bfe_i32 v2, v134, 27, 1
	v_lshlrev_b32_e32 v10, 4, v134
	v_lshrrev_b32_e32 v2, 22, v2
	v_add_u32_e32 v2, v10, v2
	v_and_b32_e32 v2, 0xfffffc00, v2
	v_sub_u32_e32 v2, v10, v2
	v_lshrrev_b32_e32 v3, 4, v2
	v_bitop3_b32 v3, v3, v2, 32 bitop3:0x6c
	v_ashrrev_i32_e32 v2, 31, v2
	v_ashrrev_i32_e32 v0, 31, v134
	v_lshrrev_b32_e32 v2, 26, v2
	v_lshrrev_b32_e32 v0, 26, v0
	v_add_u32_e32 v2, v3, v2
	s_mov_b32 s9, s91
	v_add_u32_e32 v0, v134, v0
	v_ashrrev_i32_e32 v2, 6, v2
	s_lshl_b64 s[0:1], s[8:9], 9
	v_ashrrev_i32_e32 v0, 6, v0
	s_waitcnt lgkmcnt(0)
	v_mul_i32_i24_e32 v5, 64, v2
	s_add_u32 s0, s38, s0
	v_lshlrev_b32_e32 v4, 3, v0
	v_lshlrev_b32_e32 v0, 5, v0
	v_sub_u32_e32 v3, v3, v5
	s_addc_u32 s1, s39, s1
	s_add_i32 s6, 0, 0x10000
	v_and_b32_e32 v4, 0x7ffff0, v4
	v_and_b32_e32 v0, 32, v0
	v_ashrrev_i16_sdwa v3, v212, sext(v3) dst_sel:DWORD dst_unused:UNUSED_PAD src0_sel:DWORD src1_sel:BYTE_0
	v_add_u32_e32 v17, s6, v10
	v_add_u32_sdwa v0, v0, sext(v3) dst_sel:DWORD dst_unused:UNUSED_PAD src0_sel:DWORD src1_sel:WORD_0
	v_add_lshl_u32 v4, v2, v4, 9
	v_readfirstlane_b32 s4, v17
	v_lshl_add_u32 v0, v0, 1, v4
	s_mov_b32 m0, s4
	v_add_u32_e32 v18, 0x2000, v17
	v_lshl_add_u64 v[8:9], s[0:1], 0, v[0:1]
	global_load_lds_dwordx4 v0, s[0:1]
	v_readfirstlane_b32 s0, v18
	s_ashr_i32 s21, s20, 31
	s_mov_b64 s[14:15], 0x8000
	s_mov_b32 m0, s0
	s_lshl_b64 s[0:1], s[20:21], 10
	v_readlane_b32 s12, v254, 30
	v_add_u32_e32 v15, 0, v10
	v_lshl_add_u64 v[2:3], v[8:9], 0, s[14:15]
	v_readlane_b32 s13, v254, 31
	s_add_u32 s0, s12, s0
	v_readfirstlane_b32 s4, v15
	global_load_lds_dwordx4 v[2:3], off
	v_add_u32_e32 v20, v0, v4
	s_addc_u32 s1, s13, s1
	v_mov_b32_e32 v21, v1
	s_mov_b32 m0, s4
	v_add_u32_e32 v16, 0x2000, v15
	v_lshl_add_u64 v[6:7], s[0:1], 0, v[20:21]
	global_load_lds_dwordx4 v20, s[0:1]
	v_readfirstlane_b32 s0, v16
	s_add_i32 s10, s90, 0xfffffd80
	s_mov_b32 s11, s91
	v_readlane_b32 s4, v254, 46
	s_mov_b64 s[16:17], 0x10000
	s_mov_b32 m0, s0
	s_lshl_b64 s[0:1], s[10:11], 9
	v_add_u32_e32 v13, s4, v10
	v_lshl_add_u64 v[2:3], v[6:7], 0, s[16:17]
	s_add_u32 s0, s38, s0
	v_readfirstlane_b32 s4, v13
	global_load_lds_dwordx4 v[2:3], off
	s_addc_u32 s1, s39, s1
	s_mov_b32 m0, s4
	v_add_u32_e32 v14, 0x2000, v13
	v_lshl_add_u64 v[4:5], s[0:1], 0, v[0:1]
	global_load_lds_dwordx4 v0, s[0:1]
	v_readfirstlane_b32 s0, v14
	s_mov_b32 m0, s0
	s_or_b32 s0, s20, 0x80
	s_ashr_i32 s1, s0, 31
	s_lshl_b64 s[0:1], s[0:1], 10
	v_add_u32_e32 v0, 0x4000, v15
	v_lshl_add_u64 v[2:3], v[4:5], 0, s[14:15]
	s_add_u32 s0, s12, s0
	v_readfirstlane_b32 s4, v0
	global_load_lds_dwordx4 v[2:3], off
	s_addc_u32 s1, s13, s1
	s_mov_b32 m0, s4
	v_add_u32_e32 v12, 0x6000, v15
	v_lshl_add_u64 v[2:3], s[0:1], 0, v[20:21]
	global_load_lds_dwordx4 v20, s[0:1]
	v_readfirstlane_b32 s0, v12
	v_lshl_add_u64 v[20:21], v[2:3], 0, s[16:17]
	s_mov_b32 m0, s0
	v_ashrrev_i32_e32 v131, 8, v134
	global_load_lds_dwordx4 v[20:21], off
	v_cmp_eq_u32_e32 vcc, 1, v131
	s_and_saveexec_b64 s[4:5], vcc
	s_cbranch_execz .LBB0_943
	s_barrier
